# v60 + hg_pass1 lower-bound loads hoisted out of the unit loop
# speedup vs baseline: 1.0059x; 1.0059x over previous
; __device__ __forceinline__ float sigmoidf_(float x) { return __builtin_amdgcn_rcpf(1.0f + __expf(-x)); }
; __device__ __forceinline__ void hg_pass1(Frame& F) {
;     ...
;     const int tid = F.tid, d = tid & 127, seg = tid >> 7, w = F.wave, lane = F.lane, r = lane & 31, hh = lane >> 5;
;     bf16 rq[16], rf[16], ri[16];
;     ...
;     if ((int)blockIdx.x < HGU) HG1_LOAD((int)blockIdx.x);
;     for (int u = blockIdx.x; u < HGU; u += F.G) {
;         int h, row0, nvalid; hg_decode(u, h, row0, nvalid);
;         const int hd = h * 128 + d;
;         const float lb = sigmoidf_(hglb[hd] - hglb[2048 + hd]);
.LBB0_480:
	s_add_u32 s4, s90, 0x8300000
	s_addc_u32 s5, s91, 0
	v_writelane_b32 v240, s4, 19
	v_cndmask_b32_e64 v2, 0, 1, s[0:1]
	v_lshlrev_b32_e32 v153, 4, v162
	v_writelane_b32 v240, s5, 20
	s_add_u32 s4, s90, 0x20d00000
	s_addc_u32 s5, s91, 0
	v_writelane_b32 v240, s4, 21
	s_andn2_b64 vcc, exec, s[0:1]
	s_nop 0
	v_writelane_b32 v240, s5, 22
	v_cmp_ne_u32_e64 s[4:5], 1, v2
	s_nop 1
	v_writelane_b32 v240, s4, 23
	s_nop 1
	v_writelane_b32 v240, s5, 24
	v_writelane_b32 v240, s8, 25
	v_writelane_b32 v240, s9, 26
	v_writelane_b32 v240, s76, 27
	s_nop 1
	v_writelane_b32 v240, s77, 28
	v_writelane_b32 v240, s82, 29
	s_nop 1
	v_writelane_b32 v240, s83, 30
	v_writelane_b32 v240, s80, 31
	s_nop 1
	v_writelane_b32 v240, s81, 32
	v_writelane_b32 v240, s79, 33
	s_cbranch_vccnz .LBB0_524
	v_writelane_b32 v240, s71, 34
	v_writelane_b32 v240, s84, 35
	s_add_i32 s0, 0, 0x13c00
	v_lshlrev_b32_e32 v20, 2, v18
	v_writelane_b32 v240, s85, 36
	v_writelane_b32 v240, s78, 37
	v_lshl_add_u32 v32, v0, 2, s0
	v_add_u32_e32 v33, s0, v20
	s_movk_i32 s0, 0x80
	v_writelane_b32 v240, s94, 38
	v_cmp_gt_u32_e64 s[12:13], s0, v0
	s_movk_i32 s0, 0xff
	v_writelane_b32 v240, s95, 39
	v_cmp_lt_u32_e64 s[14:15], s0, v0
	s_movk_i32 s0, 0x17f
	s_cmpk_lt_u32 s86, 0x100
	v_writelane_b32 v240, s74, 40
	v_cmp_lt_u32_e64 s[16:17], s0, v0
	s_cselect_b64 s[0:1], -1, 0
	s_lshr_b32 s4, s86, 7
	s_bfe_u32 s23, s86, 0x10006
	v_writelane_b32 v240, s75, 41
	s_cmp_lg_u32 s4, 1
	s_mov_b32 s10, s86
	s_cselect_b64 s[6:7], -1, 0
	v_writelane_b32 v240, s10, 42
	s_bitcmp1_b32 s86, 6
	v_mul_u32_u24_e32 v2, 0x48, v18
	v_writelane_b32 v240, s11, 43
	s_cselect_b64 s[10:11], -1, 0
	v_lshlrev_b32_e32 v2, 1, v2
	v_lshlrev_b32_e32 v3, 5, v24
	s_or_b64 s[6:7], s[6:7], s[10:11]
	s_lshl_b32 s10, s4, 5
	v_add3_u32 v34, 0, v2, v3
	v_writelane_b32 v240, s6, 44
	v_or_b32_e32 v3, s10, v164
	v_add_u32_e32 v2, 0, v153
	s_movk_i32 s3, 0x110
	v_writelane_b32 v240, s7, 45
	v_mad_u64_u32 v[22:23], s[6:7], v3, s3, v[2:3]
	v_lshl_or_b32 v23, s23, 5, v164
	v_mad_u32_u24 v35, v23, s3, v2
	v_lshlrev_b32_e32 v4, 2, v162
	s_add_i32 s3, 0, 0x11800
	v_or_b32_e32 v5, s10, v4
	s_movk_i32 s6, 0x90
	v_mov_b32_e32 v6, s3
	v_lshlrev_b32_e32 v3, 7, v3
	v_mad_u32_u24 v6, v23, s6, v6
	v_sub_u32_e32 v36, v22, v3
	v_mul_u32_u24_e32 v3, 0x880, v24
	v_cmp_gt_u32_e64 s[6:7], v5, v23
	v_or_b32_e32 v38, 1, v1
	v_or_b32_e32 v3, v3, v18
	s_movk_i32 s3, 0x88
	v_writelane_b32 v240, s6, 46
	v_lshl_add_u32 v53, v3, 1, 0
	v_mad_u32_u24 v3, v38, s3, v18
	v_writelane_b32 v240, s7, 47
	v_cmp_lt_u32_e64 s[6:7], v5, v23
	v_lshl_add_u32 v54, v3, 1, 0
	v_or_b32_e32 v3, 2, v5
	v_writelane_b32 v240, s6, 48
	s_ashr_i32 s3, s2, 31
	v_mov_b32_e32 v21, 0
	v_writelane_b32 v240, s7, 49
	v_cmp_gt_u32_e64 s[6:7], v3, v23
	v_or_b32_e32 v3, 3, v5
	v_add_u32_e32 v37, v6, v153
	v_writelane_b32 v240, s6, 50
	v_lshl_add_u32 v73, v5, 1, v6
	s_load_dwordx2 s[8:9], s[74:75], 0x60
	v_writelane_b32 v240, s7, 51
	v_cmp_gt_u32_e64 s[6:7], v3, v23
	v_or_b32_e32 v3, 8, v5
	v_or_b32_e32 v39, 2, v1
	v_writelane_b32 v240, s6, 52
	v_or_b32_e32 v40, 3, v1
	v_or_b32_e32 v41, 4, v1
	v_writelane_b32 v240, s7, 53
	v_cmp_gt_u32_e64 s[6:7], v3, v23
	v_or_b32_e32 v42, 5, v1
	v_or_b32_e32 v43, 6, v1
	v_writelane_b32 v240, s6, 54
	v_or_b32_e32 v44, 7, v1
	v_or_b32_e32 v45, 8, v1
	v_writelane_b32 v240, s7, 55
	v_cmp_lt_u32_e64 s[6:7], v3, v23
	v_or_b32_e32 v3, 10, v5
	v_cmp_gt_u32_e64 s[30:31], v3, v23
	v_writelane_b32 v240, s6, 56
	v_or_b32_e32 v3, 11, v5
	v_cmp_gt_u32_e64 s[34:35], v3, v23
	v_writelane_b32 v240, s7, 57
	s_lshl_b64 s[6:7], s[2:3], 9
	s_add_u32 s6, s90, s6
	v_or_b32_e32 v3, 16, v5
	s_addc_u32 s7, s91, s7
	v_cmp_gt_u32_e64 s[36:37], v3, v23
	v_cmp_lt_u32_e64 s[38:39], v3, v23
	v_or_b32_e32 v3, 18, v5
	v_lshl_add_u64 v[6:7], s[6:7], 0, v[20:21]
	s_mov_b64 s[6:7], 0x6e800000
	v_cmp_gt_u32_e64 s[40:41], v3, v23
	v_or_b32_e32 v3, 19, v5
	v_lshl_add_u64 v[24:25], v[6:7], 0, s[6:7]
	s_lshl_b64 s[6:7], s[2:3], 15
	s_lshl_b32 s3, s23, 14
	v_cmp_gt_u32_e64 s[42:43], v3, v23
	v_or_b32_e32 v3, 24, v5
	s_lshl_b32 s93, s2, 2
	s_lshl_b32 s20, s96, 2
	s_lshl_b32 s21, s2, 7
	s_lshl_b32 s22, s96, 7
	s_or_b32 s3, s6, s3
	s_lshl_b32 s4, s4, 6
	v_cmp_gt_u32_e64 s[44:45], v3, v23
	v_cmp_lt_u32_e64 s[46:47], v3, v23
	v_or_b32_e32 v3, 26, v5
	s_add_u32 s6, s4, s3
	v_cmp_gt_u32_e64 s[18:19], v3, v23
	v_or_b32_e32 v3, 27, v5
	v_lshlrev_b32_e32 v20, 8, v164
	s_addc_u32 s7, 0, s7
	v_cmp_gt_u32_e64 s[50:51], v3, v23
	v_lshl_or_b32 v3, s23, 6, v164
	v_lshl_add_u64 v[6:7], s[6:7], 0, v[20:21]
	v_and_b32_e32 v20, 32, v0
	v_mul_u32_u24_e32 v5, 0x90, v3
	v_or_b32_e32 v3, 32, v3
	v_lshrrev_b32_e32 v20, 2, v20
	v_or_b32_e32 v46, 9, v1
	v_or_b32_e32 v47, 10, v1
	v_or_b32_e32 v48, 11, v1
	v_or_b32_e32 v49, 12, v1
	v_or_b32_e32 v50, 13, v1
	v_or_b32_e32 v51, 14, v1
	v_or_b32_e32 v52, 15, v1
	v_mul_u32_u24_e32 v3, 0x90, v3
	v_or_b32_e32 v6, v6, v20
	s_mov_b32 s5, 0
	v_add_u32_e32 v55, 0x110, v54
	v_add_u32_e32 v56, 0x220, v54
	v_add_u32_e32 v57, 0x330, v54
	v_add_u32_e32 v58, 0x440, v54
	v_add_u32_e32 v59, 0x550, v54
	v_add_u32_e32 v60, 0x660, v54
	v_add_u32_e32 v61, 0x770, v54
	v_add_u32_e32 v62, 0x880, v54
	v_add_u32_e32 v63, 0x990, v54
	v_add_u32_e32 v64, 0xaa0, v54
	v_add_u32_e32 v65, 0xbb0, v54
	v_add_u32_e32 v66, 0xcc0, v54
	v_add_u32_e32 v67, 0xdd0, v54
	v_add_u32_e32 v69, 0xee0, v54
	v_lshlrev_b32_e32 v79, 14, v38
	v_lshlrev_b32_e32 v80, 14, v39
	v_lshlrev_b32_e32 v81, 14, v40
	v_lshlrev_b32_e32 v82, 14, v41
	v_lshlrev_b32_e32 v83, 14, v42
	v_lshlrev_b32_e32 v84, 14, v43
	v_lshlrev_b32_e32 v85, 14, v44
	v_lshlrev_b32_e32 v86, 14, v45
	v_lshlrev_b32_e32 v87, 14, v46
	v_lshlrev_b32_e32 v88, 14, v47
	v_lshlrev_b32_e32 v90, 14, v48
	v_lshlrev_b32_e32 v91, 14, v49
	v_lshlrev_b32_e32 v92, 14, v50
	v_lshlrev_b32_e32 v94, 14, v51
	v_lshlrev_b32_e32 v95, 14, v52
	v_lshl_add_u64 v[26:27], s[90:91], 0, v[6:7]
	s_lshl_b64 s[6:7], s[96:97], 15
	s_mov_b64 s[86:87], 0
	s_movk_i32 s3, 0x2000
	s_mov_b32 s23, 0xc1f00000
	s_mov_b32 s24, 0x800000
	s_mov_b32 s25, 0x3f317217
	s_mov_b32 s26, 0x7f800000
	v_lshlrev_b32_e32 v28, 1, v18
	s_lshl_b32 s94, s10, 1
	v_lshlrev_b32_e32 v30, 1, v4
	v_add_u32_e32 v96, v2, v5
	v_add_u32_e32 v97, v2, v3
	v_mov_b32_e32 v98, 0x41f00000
	v_bfrev_b32_e32 v99, 1
	v_mov_b32_e32 v100, 0x41b17218
	s_mov_b32 s27, s2
	s_and_b32 s4, s21, 0x780
	v_or_b32_e32 v4, s4, v18
	v_lshlrev_b32_e32 v20, 2, v4
	s_waitcnt lgkmcnt(0)
	v_lshl_add_u64 v[2:3], s[8:9], 0, v[20:21]
	v_add_co_u32_e32 v2, vcc, s3, v2
	global_load_dword v253, v20, s[8:9]
	s_nop 0
	v_addc_co_u32_e32 v3, vcc, 0, v3, vcc
	global_load_dword v254, v[2:3], off
	s_branch .LBB0_483

; __device__ __forceinline__ float bf2f(bf16 x) { return __uint_as_float(((unsigned)x) << 16); }
; __device__ __forceinline__ float sigmoidf_(float x) { return __builtin_amdgcn_rcpf(1.0f + __expf(-x)); }
; __device__ __forceinline__ void hg_pass1(Frame& F) {
;     ...
;         int h, row0, nvalid; hg_decode(u, h, row0, nvalid);
;         const int hd = h * 128 + d;
;         const float lb = sigmoidf_(hglb[hd] - hglb[2048 + hd]);
;         float q[16], kf[16], Lc[16], vv[16]; float run = 0.f;
; #pragma unroll
;         for (int i = 0; i < 16; ++i) { const int t = seg * 16 + i; const bool valid = t < nvalid;
;             const float qv = valid ? bf2f(rq[i]) : 0.f; float fp = valid ? bf2f(rf[i]) : 0.f; const float iv = valid ? bf2f(ri[i]) : 0.f;
;             fp = fminf(fmaxf(fp, -30.f), 30.f);
;             const float e = __expf(-fp), sg = __builtin_amdgcn_rcpf(1.f + e), sgn = e * sg;
;             const float f = lb + (1.f - lb) * sg;
;             const float lf = valid ? __logf(f) : 0.f;
;             run += lf; Lc[i] = run; q[i] = qv; kf[i] = valid ? (1.f - lb) * sgn : 0.f; vv[i] = iv; }
.LBB0_483:
	s_and_b32 s4, s21, 0x780
	v_or_b32_e32 v4, s4, v18
	v_lshlrev_b32_e32 v20, 2, v4
	s_waitcnt lgkmcnt(0)
	v_lshl_add_u64 v[2:3], s[8:9], 0, v[20:21]
	v_add_co_u32_e32 v2, vcc, s3, v2
	s_nop 0
	v_addc_co_u32_e32 v3, vcc, 0, v3, vcc
	s_and_b32 s29, s27, 0x7ffffff0
	s_mov_b32 s54, s27
	s_and_b32 s28, s93, 0xffffffc0
	s_add_i32 s27, s27, s96
	s_addk_i32 s29, 0x3000
	s_cmpk_gt_i32 s27, 0x107f
	s_cselect_b64 s[10:11], -1, 0
	s_cmpk_lt_i32 s27, 0x1080
	s_cselect_b32 s55, s27, s54
	s_and_b32 s52, s55, 0x7ffffff0
	s_lshl_b32 s53, s55, 2
	s_addk_i32 s52, 0x3000
	s_andn2_b32 s53, s53, 63
	s_cmpk_lt_i32 s55, 0x1000
	s_cselect_b32 s52, s53, s52
	s_cselect_b32 s84, 64, 16
	s_ashr_i32 s53, s52, 31
	s_lshl_b64 s[52:53], s[52:53], 14
	v_readlane_b32 s56, v240, 25
	s_add_u32 s52, s56, s52
	v_readlane_b32 s56, v240, 26
	s_addc_u32 s53, s56, s53
	s_lshl_b32 s55, s55, 8
	s_and_b32 s55, s55, 0xf00
	s_add_u32 s82, s52, s55
	s_waitcnt vmcnt(7)
	v_lshlrev_b32_e32 v3, 16, v113
	s_addc_u32 s83, s53, 0
	s_waitcnt vmcnt(5)
	v_lshlrev_b32_e32 v7, 16, v111
	v_max_f32_e32 v3, v3, v3
	s_cmpk_lt_i32 s54, 0x1000
	v_max_f32_e32 v7, v7, v7
	v_med3_f32 v3, v3, s23, v98
	s_cselect_b32 s95, 64, 16
	v_lshlrev_b32_e32 v20, 16, v102
	v_med3_f32 v7, v7, s23, v98
	v_mul_f32_e32 v102, 0xbfb8aa3b, v3
	v_sub_u32_e32 v3, s95, v1
	v_lshlrev_b32_e32 v6, 16, v108
	v_mul_f32_e32 v7, 0xbfb8aa3b, v7
	v_cmp_lt_i32_e64 s[52:53], 0, v3
	v_cmp_lt_i32_e64 s[54:55], 1, v3
	v_max_f32_e32 v20, v20, v20
	v_cndmask_b32_e64 v161, 0, v6, s[52:53]
	v_cndmask_b32_e64 v6, v99, v7, s[54:55]
	v_exp_f32_e32 v159, v6
	v_cndmask_b32_e64 v6, v99, v102, s[52:53]
	v_exp_f32_e32 v6, v6
	v_med3_f32 v20, v20, s23, v98
	v_mul_f32_e32 v20, 0xbfb8aa3b, v20
	v_cmp_lt_i32_e32 vcc, 2, v3
	v_lshlrev_b32_e32 v101, 16, v101
	v_max_f32_e32 v101, v101, v101
	v_cndmask_b32_e32 v7, v99, v20, vcc
	v_exp_f32_e32 v7, v7
	v_add_f32_e32 v20, 1.0, v159
	v_rcp_f32_e32 v160, v20
	v_med3_f32 v101, v101, s23, v98
	v_add_f32_e32 v102, 1.0, v7
	v_rcp_f32_e32 v158, v102
	v_mul_f32_e32 v101, 0xbfb8aa3b, v101
	v_lshlrev_b32_e32 v89, 16, v89
	v_max_f32_e32 v89, v89, v89
	v_med3_f32 v89, v89, s23, v98
	v_mul_f32_e32 v89, 0xbfb8aa3b, v89
	v_lshlrev_b32_e32 v74, 16, v74
	v_max_f32_e32 v74, v74, v74
	v_med3_f32 v74, v74, s23, v98
	v_mul_f32_e32 v74, 0xbfb8aa3b, v74
	v_lshlrev_b32_e32 v72, 16, v72
	v_max_f32_e32 v72, v72, v72
	v_med3_f32 v72, v72, s23, v98
	v_mul_f32_e32 v72, 0xbfb8aa3b, v72
	v_lshlrev_b32_e32 v71, 16, v71
	v_max_f32_e32 v71, v71, v71
	v_med3_f32 v71, v71, s23, v98
	v_mul_f32_e32 v71, 0xbfb8aa3b, v71
	v_lshlrev_b32_e32 v70, 16, v70
	v_max_f32_e32 v70, v70, v70
	v_med3_f32 v70, v70, s23, v98
	s_waitcnt vmcnt(0)
	v_sub_f32_e32 v2, v253, v254
	v_mul_f32_e32 v2, 0xbfb8aa3b, v2
	v_exp_f32_e32 v2, v2
	v_add_f32_e32 v5, 1.0, v6
	v_rcp_f32_e32 v108, v5
	v_mul_f32_e32 v70, 0xbfb8aa3b, v70
	v_add_f32_e32 v2, 1.0, v2
	v_rcp_f32_e32 v5, v2
	v_mul_f32_e32 v2, v6, v108
	v_lshlrev_b32_e32 v227, 16, v68
	s_cselect_b32 s28, s28, s29
	v_sub_f32_e32 v6, 1.0, v5
	v_fma_f32 v20, v6, v108, v5
	v_cmp_gt_f32_e64 s[56:57], s24, v20
	v_fma_f32 v102, v6, v160, v5
	v_cmp_gt_f32_e64 s[60:61], s24, v102
	v_cndmask_b32_e64 v111, 0, 32, s[56:57]
	v_ldexp_f32 v20, v20, v111
	v_cndmask_b32_e64 v113, 0, 32, s[60:61]
	v_log_f32_e32 v20, v20
	v_fma_f32 v108, v6, v158, v5
	v_ldexp_f32 v102, v102, v113
	v_cmp_gt_f32_e64 s[58:59], s24, v108
	v_log_f32_e32 v102, v102
	v_cndmask_b32_e64 v111, 0, v100, s[56:57]
	v_cndmask_b32_e64 v126, 0, 32, s[58:59]
	v_ldexp_f32 v108, v108, v126
	v_mul_f32_e32 v126, 0x3f317217, v20
	v_fma_f32 v126, v20, s25, -v126
	v_mul_f32_e32 v127, 0x3f317217, v102
	v_fmac_f32_e32 v126, 0x3377d1cf, v20
	v_fma_f32 v127, v102, s25, -v127
	v_fmac_f32_e32 v126, 0x3f317217, v20
	v_cmp_lt_f32_e64 s[56:57], |v20|, s26
	v_fmac_f32_e32 v127, 0x3377d1cf, v102
	v_fmac_f32_e32 v127, 0x3f317217, v102
	v_cndmask_b32_e64 v20, v20, v126, s[56:57]
	v_cmp_lt_f32_e64 s[56:57], |v102|, s26
	v_sub_f32_e32 v20, v20, v111
	v_add_f32_e32 v20, 0, v20
	v_cndmask_b32_e64 v102, v102, v127, s[56:57]
	v_cmp_lt_i32_e64 s[56:57], 3, v3
	v_cndmask_b32_e64 v194, 0, v20, s[52:53]
	v_log_f32_e32 v108, v108
	v_cndmask_b32_e64 v20, v99, v101, s[56:57]
	v_exp_f32_e32 v195, v20
	v_cndmask_b32_e64 v113, 0, v100, s[60:61]
	v_mul_f32_e32 v128, 0x3f317217, v108
	v_sub_f32_e32 v102, v102, v113
	v_add_f32_e32 v101, 1.0, v195
	v_rcp_f32_e32 v198, v101
	v_fma_f32 v20, v108, s25, -v128
	v_cndmask_b32_e64 v102, 0, v102, s[54:55]
	v_fmac_f32_e32 v20, 0x3377d1cf, v108
	v_add_f32_e32 v169, v102, v194
	v_fmac_f32_e32 v20, 0x3f317217, v108
	v_cmp_lt_f32_e64 s[60:61], |v108|, s26
	v_cndmask_b32_e64 v101, 0, v100, s[58:59]
	v_fma_f32 v102, v6, v198, v5
	v_cmp_lt_i32_e64 s[58:59], 4, v3
	v_cndmask_b32_e64 v20, v108, v20, s[60:61]
	v_cmp_gt_f32_e64 s[60:61], s24, v102
	v_cndmask_b32_e64 v89, v99, v89, s[58:59]
	v_exp_f32_e32 v192, v89
	v_cndmask_b32_e64 v108, 0, 32, s[60:61]
	v_ldexp_f32 v102, v102, v108
	v_log_f32_e32 v102, v102
	v_sub_f32_e32 v20, v20, v101
	v_add_f32_e32 v89, 1.0, v192
	v_cndmask_b32_e32 v20, 0, v20, vcc
	v_rcp_f32_e32 v197, v89
	v_add_f32_e32 v210, v20, v169
	v_mul_f32_e32 v20, 0x3f317217, v102
	v_fma_f32 v20, v102, s25, -v20
	v_fmac_f32_e32 v20, 0x3377d1cf, v102
	v_fmac_f32_e32 v20, 0x3f317217, v102
	v_cmp_lt_f32_e64 s[62:63], |v102|, s26
	v_fma_f32 v101, v6, v197, v5
	v_cndmask_b32_e64 v89, 0, v100, s[60:61]
	v_cndmask_b32_e64 v20, v102, v20, s[62:63]
	v_cmp_gt_f32_e64 s[62:63], s24, v101
	v_cmp_lt_i32_e64 s[60:61], 5, v3
	v_sub_f32_e32 v20, v20, v89
	v_cndmask_b32_e64 v102, 0, 32, s[62:63]
	v_ldexp_f32 v101, v101, v102
	v_log_f32_e32 v101, v101
	v_cndmask_b32_e64 v74, v99, v74, s[60:61]
; __device__ __forceinline__ float bf2f(bf16 x) { return __uint_as_float(((unsigned)x) << 16); }
; __device__ __forceinline__ void hg_pass1(Frame& F) {
;     ...
;         for (int i = 0; i < 16; ++i) { const int t = seg * 16 + i; const bool valid = t < nvalid;
;             const float qv = valid ? bf2f(rq[i]) : 0.f; float fp = valid ? bf2f(rf[i]) : 0.f; const float iv = valid ? bf2f(ri[i]) : 0.f;
;             fp = fminf(fmaxf(fp, -30.f), 30.f);
;             const float e = __expf(-fp), sg = __builtin_amdgcn_rcpf(1.f + e), sgn = e * sg;
;             const float f = lb + (1.f - lb) * sg;
;             const float lf = valid ? __logf(f) : 0.f;
;             run += lf; Lc[i] = run; q[i] = qv; kf[i] = valid ? (1.f - lb) * sgn : 0.f; vv[i] = iv; }
	v_exp_f32_e32 v190, v74
	v_cndmask_b32_e64 v20, 0, v20, s[56:57]
	v_add_f32_e32 v209, v20, v210
	v_mul_f32_e32 v20, 0x3f317217, v101
	v_fma_f32 v20, v101, s25, -v20
	v_fmac_f32_e32 v20, 0x3377d1cf, v101
	v_add_f32_e32 v74, 1.0, v190
	v_fmac_f32_e32 v20, 0x3f317217, v101
	v_rcp_f32_e32 v196, v74
	v_cmp_lt_f32_e64 s[64:65], |v101|, s26
	v_cndmask_b32_e64 v74, 0, v100, s[62:63]
	v_cmp_lt_i32_e64 s[62:63], 6, v3
	v_cndmask_b32_e64 v20, v101, v20, s[64:65]
	v_sub_f32_e32 v20, v20, v74
	v_lshlrev_b32_e32 v74, 16, v93
	v_max_f32_e32 v74, v74, v74
	v_fma_f32 v89, v6, v196, v5
	v_med3_f32 v74, v74, s23, v98
	v_cmp_gt_f32_e64 s[64:65], s24, v89
	v_mul_f32_e32 v74, 0xbfb8aa3b, v74
	v_cndmask_b32_e64 v74, v99, v74, s[62:63]
	v_cndmask_b32_e64 v101, 0, 32, s[64:65]
	v_ldexp_f32 v89, v89, v101
	v_exp_f32_e32 v188, v74
	v_log_f32_e32 v89, v89
	v_cndmask_b32_e64 v20, 0, v20, s[58:59]
	v_add_f32_e32 v208, v20, v209
	v_add_f32_e32 v74, 1.0, v188
	v_mul_f32_e32 v20, 0x3f317217, v89
	v_rcp_f32_e32 v193, v74
	v_fma_f32 v20, v89, s25, -v20
	v_fmac_f32_e32 v20, 0x3377d1cf, v89
	v_fmac_f32_e32 v20, 0x3f317217, v89
	v_cmp_lt_f32_e64 s[66:67], |v89|, s26
	v_cndmask_b32_e64 v74, 0, v100, s[64:65]
	v_cmp_lt_i32_e64 s[64:65], 7, v3
	v_cndmask_b32_e64 v20, v89, v20, s[66:67]
	v_fma_f32 v89, v6, v193, v5
	v_cmp_gt_f32_e64 s[66:67], s24, v89
	v_sub_f32_e32 v20, v20, v74
	v_lshlrev_b32_e32 v74, 16, v75
	v_cndmask_b32_e64 v93, 0, 32, s[66:67]
	v_max_f32_e32 v74, v74, v74
	v_ldexp_f32 v89, v89, v93
	v_med3_f32 v74, v74, s23, v98
	v_log_f32_e32 v89, v89
	v_mul_f32_e32 v74, 0xbfb8aa3b, v74
	v_cndmask_b32_e64 v74, v99, v74, s[64:65]
	v_exp_f32_e32 v186, v74
	v_cndmask_b32_e64 v20, 0, v20, s[60:61]
	v_add_f32_e32 v207, v20, v208
	v_mul_f32_e32 v20, 0x3f317217, v89
	v_fma_f32 v20, v89, s25, -v20
	v_fmac_f32_e32 v20, 0x3377d1cf, v89
	v_add_f32_e32 v74, 1.0, v186
	v_fmac_f32_e32 v20, 0x3f317217, v89
	v_rcp_f32_e32 v191, v74
	v_cmp_lt_f32_e64 s[68:69], |v89|, s26
	v_cndmask_b32_e64 v74, 0, v100, s[66:67]
	v_cmp_lt_i32_e64 s[66:67], 8, v3
	v_cndmask_b32_e64 v20, v89, v20, s[68:69]
	v_sub_f32_e32 v20, v20, v74
	v_lshlrev_b32_e32 v74, 16, v78
	v_max_f32_e32 v74, v74, v74
	v_fma_f32 v75, v6, v191, v5
	v_med3_f32 v74, v74, s23, v98
	v_cmp_gt_f32_e64 s[68:69], s24, v75
	v_mul_f32_e32 v74, 0xbfb8aa3b, v74
	v_cndmask_b32_e64 v74, v99, v74, s[66:67]
	v_cndmask_b32_e64 v89, 0, 32, s[68:69]
	v_ldexp_f32 v75, v75, v89
	v_exp_f32_e32 v184, v74
	v_log_f32_e32 v75, v75
	v_cndmask_b32_e64 v20, 0, v20, s[62:63]
	v_add_f32_e32 v206, v20, v207
	v_add_f32_e32 v74, 1.0, v184
	v_mul_f32_e32 v20, 0x3f317217, v75
	v_rcp_f32_e32 v189, v74
	v_fma_f32 v20, v75, s25, -v20
	v_fmac_f32_e32 v20, 0x3377d1cf, v75
	v_fmac_f32_e32 v20, 0x3f317217, v75
	v_cmp_lt_f32_e64 s[70:71], |v75|, s26
	v_cndmask_b32_e64 v74, 0, v100, s[68:69]
	v_cmp_lt_i32_e64 s[68:69], 9, v3
	v_cndmask_b32_e64 v20, v75, v20, s[70:71]
	v_fma_f32 v75, v6, v189, v5
	v_cmp_gt_f32_e64 s[70:71], s24, v75
	v_cndmask_b32_e64 v72, v99, v72, s[68:69]
	v_sub_f32_e32 v20, v20, v74
	v_cndmask_b32_e64 v78, 0, 32, s[70:71]
	v_ldexp_f32 v75, v75, v78
	v_log_f32_e32 v75, v75
	v_exp_f32_e32 v177, v72
	v_cndmask_b32_e64 v20, 0, v20, s[64:65]
	v_add_f32_e32 v205, v20, v206
	v_mul_f32_e32 v20, 0x3f317217, v75
	v_fma_f32 v20, v75, s25, -v20
	v_fmac_f32_e32 v20, 0x3377d1cf, v75
	v_add_f32_e32 v72, 1.0, v177
	v_fmac_f32_e32 v20, 0x3f317217, v75
	v_rcp_f32_e32 v187, v72
	v_cmp_lt_f32_e64 s[72:73], |v75|, s26
	v_cndmask_b32_e64 v72, 0, v100, s[70:71]
	v_cmp_lt_i32_e64 s[70:71], 10, v3
	v_cndmask_b32_e64 v20, v75, v20, s[72:73]
	v_sub_f32_e32 v20, v20, v72
	v_lshlrev_b32_e32 v72, 16, v77
	v_max_f32_e32 v72, v72, v72
	v_fma_f32 v74, v6, v187, v5
	v_med3_f32 v72, v72, s23, v98
	v_cmp_gt_f32_e64 s[72:73], s24, v74
	v_mul_f32_e32 v72, 0xbfb8aa3b, v72
	v_cndmask_b32_e64 v72, v99, v72, s[70:71]
	v_cndmask_b32_e64 v75, 0, 32, s[72:73]
	v_ldexp_f32 v74, v74, v75
	v_exp_f32_e32 v175, v72
	v_log_f32_e32 v74, v74
	v_cndmask_b32_e64 v20, 0, v20, s[66:67]
	v_add_f32_e32 v204, v20, v205
	v_add_f32_e32 v72, 1.0, v175
	v_mul_f32_e32 v20, 0x3f317217, v74
	v_rcp_f32_e32 v185, v72
	v_fma_f32 v20, v74, s25, -v20
	v_fmac_f32_e32 v20, 0x3377d1cf, v74
	v_fmac_f32_e32 v20, 0x3f317217, v74
	v_cmp_lt_f32_e64 s[74:75], |v74|, s26
	v_cndmask_b32_e64 v72, 0, v100, s[72:73]
	v_cmp_lt_i32_e64 s[72:73], 11, v3
	v_cndmask_b32_e64 v20, v74, v20, s[74:75]
	v_fma_f32 v74, v6, v185, v5
	v_cmp_gt_f32_e64 s[74:75], s24, v74
	v_cndmask_b32_e64 v71, v99, v71, s[72:73]
	v_sub_f32_e32 v20, v20, v72
	v_cndmask_b32_e64 v75, 0, 32, s[74:75]
	v_ldexp_f32 v74, v74, v75
	v_log_f32_e32 v74, v74
	v_exp_f32_e32 v173, v71
	v_cndmask_b32_e64 v20, 0, v20, s[68:69]
	v_add_f32_e32 v203, v20, v204
	v_mul_f32_e32 v20, 0x3f317217, v74
	v_fma_f32 v20, v74, s25, -v20
	v_fmac_f32_e32 v20, 0x3377d1cf, v74
	v_add_f32_e32 v71, 1.0, v173
	v_fmac_f32_e32 v20, 0x3f317217, v74
	v_rcp_f32_e32 v179, v71
	v_cmp_lt_f32_e64 s[76:77], |v74|, s26
	v_cndmask_b32_e64 v71, 0, v100, s[74:75]
	v_cmp_lt_i32_e64 s[74:75], 12, v3
	v_cndmask_b32_e64 v20, v74, v20, s[76:77]
	v_sub_f32_e32 v20, v20, v71
	v_lshlrev_b32_e32 v71, 16, v76
	v_max_f32_e32 v71, v71, v71
	v_fma_f32 v72, v6, v179, v5
	v_med3_f32 v71, v71, s23, v98
	v_cmp_gt_f32_e64 s[76:77], s24, v72
	v_mul_f32_e32 v71, 0xbfb8aa3b, v71
	v_cndmask_b32_e64 v71, v99, v71, s[74:75]
	v_cndmask_b32_e64 v74, 0, 32, s[76:77]
	v_ldexp_f32 v72, v72, v74
	v_exp_f32_e32 v172, v71
	v_log_f32_e32 v72, v72
	v_cndmask_b32_e64 v20, 0, v20, s[70:71]
	v_add_f32_e32 v201, v20, v203
	v_add_f32_e32 v71, 1.0, v172
	v_mul_f32_e32 v20, 0x3f317217, v72
	v_rcp_f32_e32 v176, v71
	v_fma_f32 v20, v72, s25, -v20
; __device__ __forceinline__ float bf2f(bf16 x) { return __uint_as_float(((unsigned)x) << 16); }
; __device__ __forceinline__ void hg_pass1(Frame& F) {
;     ...
;         for (int i = 0; i < 16; ++i) { const int t = seg * 16 + i; const bool valid = t < nvalid;
;             const float qv = valid ? bf2f(rq[i]) : 0.f; float fp = valid ? bf2f(rf[i]) : 0.f; const float iv = valid ? bf2f(ri[i]) : 0.f;
;             fp = fminf(fmaxf(fp, -30.f), 30.f);
;             const float e = __expf(-fp), sg = __builtin_amdgcn_rcpf(1.f + e), sgn = e * sg;
;             const float f = lb + (1.f - lb) * sg;
;             const float lf = valid ? __logf(f) : 0.f;
;             run += lf; Lc[i] = run; q[i] = qv; kf[i] = valid ? (1.f - lb) * sgn : 0.f; vv[i] = iv; }
;         { const int un = u + F.G < HGU ? u + F.G : u; HG1_LOAD(un); }
	v_fmac_f32_e32 v20, 0x3377d1cf, v72
	v_fmac_f32_e32 v20, 0x3f317217, v72
	v_cmp_lt_f32_e64 s[78:79], |v72|, s26
	v_cndmask_b32_e64 v71, 0, v100, s[76:77]
	v_mul_f32_e32 v2, v6, v2
	v_cndmask_b32_e64 v20, v72, v20, s[78:79]
	v_fma_f32 v72, v6, v176, v5
	v_cmp_lt_i32_e64 s[78:79], 13, v3
	v_cmp_gt_f32_e64 s[76:77], s24, v72
	v_sub_f32_e32 v20, v20, v71
	v_cndmask_b32_e64 v70, v99, v70, s[78:79]
	v_cndmask_b32_e64 v74, 0, 32, s[76:77]
	v_exp_f32_e32 v171, v70
	v_ldexp_f32 v72, v72, v74
	v_log_f32_e32 v72, v72
	v_cndmask_b32_e64 v20, 0, v20, s[72:73]
	v_add_f32_e32 v70, 1.0, v171
	v_rcp_f32_e32 v174, v70
	v_add_f32_e32 v200, v20, v201
	v_mul_f32_e32 v20, 0x3f317217, v72
	v_fma_f32 v20, v72, s25, -v20
	v_fmac_f32_e32 v20, 0x3377d1cf, v72
	v_fmac_f32_e32 v20, 0x3f317217, v72
	v_cmp_lt_f32_e64 s[80:81], |v72|, s26
	v_fma_f32 v71, v6, v174, v5
	v_cndmask_b32_e64 v70, 0, v100, s[76:77]
	v_cndmask_b32_e64 v20, v72, v20, s[80:81]
	v_cmp_gt_f32_e64 s[80:81], s24, v71
	v_sub_f32_e32 v20, v20, v70
	v_cndmask_b32_e64 v20, 0, v20, s[74:75]
	v_cndmask_b32_e64 v72, 0, 32, s[80:81]
	v_ldexp_f32 v71, v71, v72
	v_log_f32_e32 v211, v71
	v_add_f32_e32 v199, v20, v200
	v_cmp_lt_i32_e64 s[76:77], 14, v3
	v_mul_f32_e32 v20, 0x3f317217, v211
	v_fma_f32 v226, v211, s25, -v20
	v_lshlrev_b32_e32 v20, 16, v29
	v_max_f32_e32 v20, v20, v20
	v_med3_f32 v20, v20, s23, v98
	v_mul_f32_e32 v20, 0xbfb8aa3b, v20
	v_mov_b32_e32 v29, v21
	v_cndmask_b32_e64 v20, v99, v20, s[76:77]
	v_lshl_add_u64 v[146:147], s[82:83], 0, v[28:29]
	v_cmp_gt_u32_e64 s[82:83], s84, v1
	v_exp_f32_e32 v170, v20
	v_fmac_f32_e32 v226, 0x3377d1cf, v211
	v_cndmask_b32_e64 v20, 0, v19, s[82:83]
	v_lshl_add_u64 v[70:71], v[146:147], 0, v[20:21]
	v_add_co_u32_e64 v74, s[82:83], s3, v70
	v_fmac_f32_e32 v226, 0x3f317217, v211
	s_nop 0
	v_addc_co_u32_e64 v75, s[82:83], 0, v71, s[82:83]
	v_cmp_gt_u32_e64 s[82:83], s84, v38
	s_nop 1
	v_cndmask_b32_e64 v20, 0, v79, s[82:83]
	v_lshl_add_u64 v[76:77], v[146:147], 0, v[20:21]
	v_add_co_u32_e64 v128, s[82:83], s3, v76
	s_nop 1
	v_addc_co_u32_e64 v129, s[82:83], 0, v77, s[82:83]
	v_cmp_gt_u32_e64 s[82:83], s84, v39
	s_nop 1
	v_cndmask_b32_e64 v20, 0, v80, s[82:83]
	v_lshl_add_u64 v[132:133], v[146:147], 0, v[20:21]
	v_add_co_u32_e64 v130, s[82:83], s3, v132
	s_nop 1
	v_addc_co_u32_e64 v131, s[82:83], 0, v133, s[82:83]
	v_cmp_gt_u32_e64 s[82:83], s84, v40
	s_nop 1
	v_cndmask_b32_e64 v20, 0, v81, s[82:83]
	v_lshl_add_u64 v[134:135], v[146:147], 0, v[20:21]
	v_add_co_u32_e64 v136, s[82:83], s3, v134
	s_nop 1
	v_addc_co_u32_e64 v137, s[82:83], 0, v135, s[82:83]
	v_cmp_gt_u32_e64 s[82:83], s84, v41
	global_load_ushort v113, v[74:75], off offset:-4096
	global_load_ushort v126, v[74:75], off
	global_load_ushort v111, v[128:129], off offset:-4096
	global_load_ushort v127, v[128:129], off
	global_load_ushort v102, v[130:131], off offset:-4096
	s_nop 0
	global_load_ushort v128, v[130:131], off
	global_load_ushort v101, v[136:137], off offset:-4096
	global_load_ushort v129, v[136:137], off
	v_cndmask_b32_e64 v20, 0, v82, s[82:83]
	v_lshl_add_u64 v[74:75], v[146:147], 0, v[20:21]
	v_add_co_u32_e64 v138, s[82:83], s3, v74
	s_nop 1
	v_addc_co_u32_e64 v139, s[82:83], 0, v75, s[82:83]
	v_cmp_gt_u32_e64 s[82:83], s84, v42
	s_nop 1
	v_cndmask_b32_e64 v20, 0, v83, s[82:83]
	v_lshl_add_u64 v[136:137], v[146:147], 0, v[20:21]
	v_add_co_u32_e64 v140, s[82:83], s3, v136
	s_nop 1
	v_addc_co_u32_e64 v141, s[82:83], 0, v137, s[82:83]
	v_cmp_gt_u32_e64 s[82:83], s84, v43
	s_nop 1
	v_cndmask_b32_e64 v20, 0, v84, s[82:83]
	v_lshl_add_u64 v[142:143], v[146:147], 0, v[20:21]
	v_add_co_u32_e64 v144, s[82:83], s3, v142
	s_nop 1
	v_addc_co_u32_e64 v145, s[82:83], 0, v143, s[82:83]
	v_cmp_gt_u32_e64 s[82:83], s84, v44
	s_nop 1
	v_cndmask_b32_e64 v20, 0, v85, s[82:83]
	v_lshl_add_u64 v[148:149], v[146:147], 0, v[20:21]
	global_load_ushort v108, v[70:71], off
	global_load_ushort v130, v[76:77], off
	global_load_ushort v131, v[132:133], off
	s_nop 0
	global_load_ushort v132, v[134:135], off
	global_load_ushort v133, v[74:75], off
	s_nop 0
	global_load_ushort v134, v[136:137], off
	global_load_ushort v135, v[142:143], off
	s_nop 0
	global_load_ushort v136, v[148:149], off
	v_add_co_u32_e64 v70, s[82:83], s3, v148
	s_nop 1
	v_addc_co_u32_e64 v71, s[82:83], 0, v149, s[82:83]
	v_cmp_gt_u32_e64 s[82:83], s84, v45
	global_load_ushort v89, v[138:139], off offset:-4096
	global_load_ushort v137, v[138:139], off
	global_load_ushort v74, v[140:141], off offset:-4096
	s_nop 0
	global_load_ushort v138, v[140:141], off
	global_load_ushort v93, v[144:145], off offset:-4096
	global_load_ushort v139, v[144:145], off
	global_load_ushort v75, v[70:71], off offset:-4096
	s_nop 0
	global_load_ushort v140, v[70:71], off
	v_cndmask_b32_e64 v20, 0, v86, s[82:83]
	v_lshl_add_u64 v[148:149], v[146:147], 0, v[20:21]
	v_add_co_u32_e64 v70, s[82:83], s3, v148
	s_nop 1
	v_addc_co_u32_e64 v71, s[82:83], 0, v149, s[82:83]
	v_cmp_gt_u32_e64 s[82:83], s84, v46
	s_nop 1
	v_cndmask_b32_e64 v20, 0, v87, s[82:83]
	v_lshl_add_u64 v[150:151], v[146:147], 0, v[20:21]
	v_add_co_u32_e64 v76, s[82:83], s3, v150
	s_nop 1
	v_addc_co_u32_e64 v77, s[82:83], 0, v151, s[82:83]
	v_cmp_gt_u32_e64 s[82:83], s84, v47
	s_nop 1
	v_cndmask_b32_e64 v20, 0, v88, s[82:83]
	v_lshl_add_u64 v[154:155], v[146:147], 0, v[20:21]
	v_add_co_u32_e64 v144, s[82:83], s3, v154
	s_nop 1
; __device__ __forceinline__ unsigned f2bf(float f) { return cvt_pk_bf16(f, 0.f) & 0xffffu; }
; __device__ __forceinline__ void hg_pass1(Frame& F) {
;     ...
;             run += lf; Lc[i] = run; q[i] = qv; kf[i] = valid ? (1.f - lb) * sgn : 0.f; vv[i] = iv; }
;         { const int un = u + F.G < HGU ? u + F.G : u; HG1_LOAD(un); }
;         SEG[seg * 128 + d] = run;
;         __syncthreads();
;         const float s0 = SEG[d], s1 = SEG[128 + d], s2 = SEG[256 + d], s3 = SEG[384 + d];
;         const float base = (seg > 0 ? s0 : 0.f) + (seg > 1 ? s1 : 0.f) + (seg > 2 ? s2 : 0.f);
;         const float Lm = s0 + s1, Lend = Lm + s2 + s3;
;         const float eLm = __expf(Lm), eEnd = __expf(Lend - Lm);
;         unsigned kep[8], vtp[8];
; #pragma unroll
;         for (int i = 0; i < 16; i += 2) {
;             float ke2[2];
; #pragma unroll
;             for (int ii = 0; ii < 2; ++ii) { const int t = seg * 16 + i + ii; const float Lt = base + Lc[i + ii];
;                 const float e1 = __expf(Lt - Lm), e2 = __expf(Lm - Lt);
;                 const float qt = q[i + ii] * e1, kt = kf[i + ii] * e2;
;                 QT[t * 136 + d] = (bf16)f2bf(qt); KT[t * 136 + d] = (bf16)f2bf(kt);
;                 if (t < nvalid) Q0[(size_t)(row0 + t) * DH + hd] = (bf16)f2bf(qt * eLm);
	v_addc_co_u32_e64 v145, s[82:83], 0, v155, s[82:83]
	v_cmp_gt_u32_e64 s[82:83], s84, v48
	s_nop 1
	v_cndmask_b32_e64 v20, 0, v90, s[82:83]
	v_lshl_add_u64 v[156:157], v[146:147], 0, v[20:21]
	v_add_co_u32_e64 v212, s[82:83], s3, v156
	s_nop 1
	v_addc_co_u32_e64 v213, s[82:83], 0, v157, s[82:83]
	v_cmp_gt_u32_e64 s[82:83], s84, v49
	global_load_ushort v78, v[70:71], off offset:-4096
	global_load_ushort v141, v[70:71], off
	global_load_ushort v72, v[76:77], off offset:-4096
	global_load_ushort v142, v[76:77], off
	s_nop 0
	global_load_ushort v77, v[144:145], off offset:-4096
	global_load_ushort v143, v[144:145], off
	global_load_ushort v71, v[212:213], off offset:-4096
	s_nop 0
	global_load_ushort v144, v[212:213], off
	v_cndmask_b32_e64 v20, 0, v91, s[82:83]
	v_lshl_add_u64 v[212:213], v[146:147], 0, v[20:21]
	v_add_co_u32_e64 v214, s[82:83], s3, v212
	s_nop 1
	v_addc_co_u32_e64 v215, s[82:83], 0, v213, s[82:83]
	v_cmp_gt_u32_e64 s[82:83], s84, v50
	s_nop 1
	v_cndmask_b32_e64 v20, 0, v92, s[82:83]
	v_lshl_add_u64 v[216:217], v[146:147], 0, v[20:21]
	v_add_co_u32_e64 v218, s[82:83], s3, v216
	s_nop 1
	v_addc_co_u32_e64 v219, s[82:83], 0, v217, s[82:83]
	v_cmp_gt_u32_e64 s[82:83], s84, v51
	s_nop 1
	v_cndmask_b32_e64 v20, 0, v94, s[82:83]
	v_lshl_add_u64 v[220:221], v[146:147], 0, v[20:21]
	v_add_co_u32_e64 v222, s[82:83], s3, v220
	s_nop 1
	v_addc_co_u32_e64 v223, s[82:83], 0, v221, s[82:83]
	v_cmp_gt_u32_e64 s[82:83], s84, v52
	s_nop 1
	v_cndmask_b32_e64 v20, 0, v95, s[82:83]
	v_lshl_add_u64 v[224:225], v[146:147], 0, v[20:21]
	global_load_ushort v145, v[148:149], off
	global_load_ushort v146, v[150:151], off
	global_load_ushort v147, v[154:155], off
	s_nop 0
	global_load_ushort v148, v[156:157], off
	global_load_ushort v149, v[212:213], off
	global_load_ushort v150, v[216:217], off
	global_load_ushort v151, v[220:221], off
	global_load_ushort v152, v[224:225], off
	v_add_co_u32_e64 v212, s[82:83], s3, v224
	v_add_f32_e32 v20, 1.0, v170
	s_nop 0
	v_addc_co_u32_e64 v213, s[82:83], 0, v225, s[82:83]
	global_load_ushort v76, v[214:215], off offset:-4096
	global_load_ushort v154, v[214:215], off
	global_load_ushort v70, v[218:219], off offset:-4096
	global_load_ushort v155, v[218:219], off
	global_load_ushort v29, v[222:223], off offset:-4096
	global_load_ushort v156, v[222:223], off
	global_load_ushort v68, v[212:213], off offset:-4096
	global_load_ushort v157, v[212:213], off
	v_rcp_f32_e32 v215, v20
	v_cmp_lt_f32_e64 s[82:83], |v211|, s26
	v_cndmask_b32_e64 v222, 0, v2, s[52:53]
	v_fma_f32 v212, v6, v215, v5
	v_cndmask_b32_e64 v20, v211, v226, s[82:83]
	v_cndmask_b32_e64 v211, 0, v100, s[80:81]
	v_cmp_gt_f32_e64 s[82:83], s24, v212
	v_sub_f32_e32 v20, v20, v211
	v_max_f32_e32 v211, v227, v227
	v_cndmask_b32_e64 v213, 0, 32, s[82:83]
	v_med3_f32 v211, v211, s23, v98
	v_ldexp_f32 v212, v212, v213
	v_mul_f32_e32 v211, 0xbfb8aa3b, v211
	v_cmp_lt_i32_e64 s[80:81], 15, v3
	v_log_f32_e32 v212, v212
	v_cndmask_b32_e64 v20, 0, v20, s[78:79]
	v_cndmask_b32_e64 v3, v99, v211, s[80:81]
	v_exp_f32_e32 v211, v3
	v_add_f32_e32 v219, v20, v199
	v_mul_f32_e32 v20, 0x3f317217, v212
	v_fma_f32 v3, v212, s25, -v20
	v_add_f32_e32 v20, 1.0, v211
	v_rcp_f32_e32 v213, v20
	v_fmac_f32_e32 v3, 0x3377d1cf, v212
	v_fmac_f32_e32 v3, 0x3f317217, v212
	v_cmp_lt_f32_e64 s[84:85], |v212|, s26
	v_fmac_f32_e32 v5, v6, v213
	v_cndmask_b32_e64 v20, 0, v100, s[82:83]
	v_cmp_gt_f32_e64 s[82:83], s24, v5
	v_cndmask_b32_e64 v3, v212, v3, s[84:85]
	v_sub_f32_e32 v3, v3, v20
	v_cndmask_b32_e64 v212, 0, 32, s[82:83]
	v_ldexp_f32 v5, v5, v212
	v_log_f32_e32 v5, v5
	v_cndmask_b32_e64 v3, 0, v3, s[76:77]
	v_add_f32_e32 v218, v3, v219
	v_mul_f32_e32 v3, 0x3f317217, v5
	v_fma_f32 v3, v5, s25, -v3
	v_fmac_f32_e32 v3, 0x3377d1cf, v5
	v_fmac_f32_e32 v3, 0x3f317217, v5
	v_cmp_lt_f32_e64 s[84:85], |v5|, s26
	s_nop 1
	v_cndmask_b32_e64 v3, v5, v3, s[84:85]
	v_cndmask_b32_e64 v5, 0, v100, s[82:83]
	v_sub_f32_e32 v3, v3, v5
	v_cndmask_b32_e64 v3, 0, v3, s[80:81]
	v_add_f32_e32 v216, v3, v218
	ds_write_b32 v32, v216
	s_waitcnt lgkmcnt(0)
	s_barrier
	ds_read2st64_b32 v[220:221], v33 offset1:2
	ds_read2st64_b32 v[2:3], v33 offset0:4 offset1:6
	v_readlane_b32 s82, v240, 21
	v_readlane_b32 s83, v240, 22
	s_waitcnt lgkmcnt(1)
	v_cndmask_b32_e64 v5, v220, 0, s[12:13]
	v_cndmask_b32_e64 v20, 0, v221, s[14:15]
	v_add_f32_e32 v5, v5, v20
	s_waitcnt lgkmcnt(0)
	v_cndmask_b32_e64 v20, 0, v2, s[16:17]
	v_add_f32_e32 v212, v220, v221
	v_add_f32_e32 v217, v5, v20
	v_mul_f32_e32 v5, 0x3fb8aa3b, v212
	v_exp_f32_e32 v214, v5
	v_add_f32_e32 v5, v194, v217
	v_sub_f32_e32 v20, v5, v212
	v_mul_f32_e32 v20, 0x3fb8aa3b, v20
	v_sub_f32_e32 v5, v212, v5
	v_exp_f32_e32 v194, v20
	v_mul_f32_e32 v5, 0x3fb8aa3b, v5
	v_exp_f32_e32 v220, v5
	v_lshlrev_b32_e32 v20, 1, v4
	v_mul_f32_e32 v161, v161, v194
	v_lshl_add_u64 v[4:5], s[82:83], 0, v[20:21]
	v_mul_f32_e32 v20, v222, v220
	v_cvt_pk_bf16_f32 v194, v161, s0
	ds_write_b16 v53, v194
	v_cvt_pk_bf16_f32 v194, v20, s0
	v_cmp_gt_u32_e64 s[82:83], s95, v1
	ds_write_b16 v53, v194 offset:17408
	s_and_saveexec_b64 s[84:85], s[82:83]
	s_cbranch_execz .LBB0_485
	v_add_u32_e32 v220, s28, v1
	v_ashrrev_i32_e32 v221, 31, v220
	v_lshlrev_b64 v[220:221], 12, v[220:221]
	v_mul_f32_e32 v161, v214, v161
	v_lshl_add_u64 v[220:221], v[4:5], 0, v[220:221]
	v_cvt_pk_bf16_f32 v161, v161, s0
	global_store_short v[220:221], v161, off
